# decode step: next unit's state tile (13 of 16 pieces) requested right after this unit's last state store
# baseline (speedup 1.0000x reference)
; template <bool WITH_O> __device__ __forceinline__ void gla_sample(LAS unsigned char* lds, int uidx, const float* PRS, const float* GLRP, const float* w2, const float* gb, const float* gn, ...
;     ...
;     const size_t sb = ((size_t)(s * 4 + h) * DK) * DV + (tid & 63) * 4; f32x4 S[16];
; #pragma unroll
;     for (int kk = 0; kk < 16; ++kk) S[kk] = __builtin_nontemporal_load((const f32x4*)(s_in + sb + (size_t)(16 * wid + kk) * DV));
.LBB0_360:
	s_cmp_eq_u32 s79, 1
	s_cbranch_scc0 .Lgs_small
	v_mov_b32_e32 v60, v142
	v_mov_b32_e32 v61, v143
	v_mov_b32_e32 v62, v144
	v_mov_b32_e32 v63, v145
	v_mov_b32_e32 v56, v146
	v_mov_b32_e32 v57, v147
	v_mov_b32_e32 v58, v148
	v_mov_b32_e32 v59, v149
	v_mov_b32_e32 v52, v150
	v_mov_b32_e32 v53, v151
	v_mov_b32_e32 v54, v152
	v_mov_b32_e32 v55, v153
	v_mov_b32_e32 v48, v154
	v_mov_b32_e32 v49, v155
	v_mov_b32_e32 v50, v156
	v_mov_b32_e32 v51, v157
	v_mov_b32_e32 v44, v178
	v_mov_b32_e32 v45, v179
	v_mov_b32_e32 v46, v180
	v_mov_b32_e32 v47, v181
	v_mov_b32_e32 v40, v182
	v_mov_b32_e32 v41, v183
	v_mov_b32_e32 v42, v184
	v_mov_b32_e32 v43, v185
	v_mov_b32_e32 v36, v186
	v_mov_b32_e32 v37, v187
	v_mov_b32_e32 v38, v188
	v_mov_b32_e32 v39, v189
	v_mov_b32_e32 v32, v190
	v_mov_b32_e32 v33, v191
	v_mov_b32_e32 v34, v192
	v_mov_b32_e32 v35, v193
	v_mov_b32_e32 v28, v194
	v_mov_b32_e32 v29, v195
	v_mov_b32_e32 v30, v196
	v_mov_b32_e32 v31, v197
	v_mov_b32_e32 v24, v198
	v_mov_b32_e32 v25, v199
	v_mov_b32_e32 v26, v200
	v_mov_b32_e32 v27, v201
	v_mov_b32_e32 v20, v202
	v_mov_b32_e32 v21, v203
	v_mov_b32_e32 v22, v204
	v_mov_b32_e32 v23, v205
	v_mov_b32_e32 v16, v206
	v_mov_b32_e32 v17, v207
	v_mov_b32_e32 v18, v208
	v_mov_b32_e32 v19, v209
	v_mov_b32_e32 v12, v228
	v_mov_b32_e32 v13, v229
	v_mov_b32_e32 v14, v230
	v_mov_b32_e32 v15, v231
	v_mov_b32_e32 v8, v232
	v_mov_b32_e32 v9, v233
	v_mov_b32_e32 v10, v234
	v_mov_b32_e32 v11, v235
	v_mov_b32_e32 v4, v236
	v_mov_b32_e32 v5, v237
	v_mov_b32_e32 v6, v238
	v_mov_b32_e32 v7, v239
	v_mov_b32_e32 v0, v240
	v_mov_b32_e32 v1, v241
	v_mov_b32_e32 v2, v242
	v_mov_b32_e32 v3, v243
.Lgs_small:
	s_ashr_i32 s100, s55, 2
	s_mul_i32 s100, s100, 0x6400
	s_and_b32 s101, s55, 3
	s_lshl_b32 s101, s101, 10
	s_add_u32 s100, s100, s101
	s_add_u32 s98, s22, s100
	s_addc_u32 s99, s23, 0
	v_lshlrev_b32_e32 v196, 2, v121
	v_add_u32_e32 v196, 0x4000, v196
	v_and_b32_e32 v197, 0xff, v112
	v_lshlrev_b32_e32 v197, 2, v197
	v_add_u32_e32 v198, 0x5000, v197
	global_load_dwordx4 v[180:183], v196, s[98:99]
	global_load_dword v200, v198, s[98:99]
	s_add_u32 s100, s98, 0x320000
	s_addc_u32 s101, s99, 0
	global_load_dwordx4 v[184:187], v196, s[100:101]
	global_load_dword v201, v198, s[100:101]
	s_add_u32 s100, s98, 0x640000
	s_addc_u32 s101, s99, 0
	global_load_dwordx4 v[188:191], v196, s[100:101]
	global_load_dword v202, v198, s[100:101]
	s_add_u32 s100, s98, 0x960000
	s_addc_u32 s101, s99, 0
	global_load_dwordx4 v[192:195], v196, s[100:101]
	global_load_dword v203, v198, s[100:101]
	s_and_b32 s100, s55, 3
	s_lshl_b32 s100, s100, 10
	s_add_u32 s100, s2, s100
	s_addc_u32 s101, s3, 0
	global_load_dword v204, v197, s[100:101]
	s_ashr_i32 s8, s55, 2
	s_cmp_eq_u32 s79, 1
	s_cbranch_scc1 .Lgs_loaded
	s_cmp_eq_u32 s79, 2
	s_cbranch_scc1 .Lgs_last3
	v_lshl_add_u64 v[0:1], s[24:25], 0, v[114:115]
	v_add_co_u32_e32 v2, vcc, 0x1000, v0
	global_load_dwordx4 v[60:63], v[0:1], off nt
	global_load_dwordx4 v[56:59], v[0:1], off offset:1024 nt
	global_load_dwordx4 v[52:55], v[0:1], off offset:2048 nt
	global_load_dwordx4 v[48:51], v[0:1], off offset:3072 nt
	v_addc_co_u32_e32 v3, vcc, 0, v1, vcc
	global_load_dwordx4 v[44:47], v[2:3], off nt
	global_load_dwordx4 v[40:43], v[2:3], off offset:1024 nt
	global_load_dwordx4 v[36:39], v[2:3], off offset:2048 nt
	global_load_dwordx4 v[32:35], v[2:3], off offset:3072 nt
	v_add_co_u32_e32 v2, vcc, s59, v0
	s_ashr_i32 s8, s55, 2
	s_nop 0
	v_addc_co_u32_e32 v3, vcc, 0, v1, vcc
	v_add_co_u32_e32 v0, vcc, 0x3000, v0
	global_load_dwordx4 v[28:31], v[2:3], off nt
	global_load_dwordx4 v[24:27], v[2:3], off offset:1024 nt
	global_load_dwordx4 v[20:23], v[2:3], off offset:2048 nt
	global_load_dwordx4 v[16:19], v[2:3], off offset:3072 nt
	v_addc_co_u32_e32 v1, vcc, 0, v1, vcc
	global_load_dwordx4 v[12:15], v[0:1], off nt
	global_load_dwordx4 v[8:11], v[0:1], off offset:1024 nt
	global_load_dwordx4 v[4:7], v[0:1], off offset:2048 nt
	s_nop 0
	global_load_dwordx4 v[0:3], v[0:1], off offset:3072 nt
	s_branch .Lgs_loaded
.Lgs_last3:
	v_lshl_add_u64 v[0:1], s[24:25], 0, v[114:115]
	v_add_co_u32_e32 v0, vcc, 0x3000, v0
	s_nop 1
	v_addc_co_u32_e32 v1, vcc, 0, v1, vcc
	global_load_dwordx4 v[8:11], v[0:1], off offset:1024 nt
	global_load_dwordx4 v[4:7], v[0:1], off offset:2048 nt
	global_load_dwordx4 v[0:3], v[0:1], off offset:3072 nt
; __device__ __forceinline__ float logsig_f(float z) { return fminf(z, 0.f) - __logf(1.f + __expf(-fabsf(z))); }
; template <bool WITH_O> __device__ __forceinline__ void gla_sample(LAS unsigned char* lds, int uidx, const float* PRS, const float* GLRP, const float* w2, const float* gb, const float* gn, ...
;     ...
;     if (tid < DK) { const int col = h * DK + tid; float z = gb[col];
; #pragma unroll
;         for (int rr = 0; rr < RANK; ++rr) { float g = 0.f;
; #pragma unroll
;             for (int sp = 0; sp < NSP1; ++sp) g += GLRP[((size_t)sp * MPAD + row) * RANK + rr];
;             z += g * w2[rr * QKD + col]; }
;         smA[tid] = __expf(logsig_f(z) * (1.f / 16.f)); smK[tid] = prs_sum(PRS, s, 3584 + col); if (WITH_O) smQ[tid] = prs_sum(PRS, s, 3072 + col) * 0.08838834764831845f; }
.Lgs_loaded:
	s_mov_b32 s79, 0
	s_mul_hi_i32 s49, s8, 0x6400
	s_mul_i32 s48, s8, 0x6400
	s_and_saveexec_b64 s[6:7], s[42:43]
	s_xor_b64 s[6:7], exec, s[6:7]
	s_or_saveexec_b64 s[52:53], s[6:7]
	s_and_b32 s6, s55, 3
	s_add_i32 s34, s8, 0x2000
	v_mov_b64_e32 v[72:73], s[48:49]
	s_xor_b64 exec, exec, s[52:53]
	s_cbranch_execz .LBB0_362
	s_ashr_i32 s35, s34, 31
	v_lshl_add_u32 v64, s6, 7, v112
	s_lshl_b64 s[46:47], s[34:35], 6
	v_lshlrev_b32_e32 v64, 2, v64
	s_add_u32 s46, s30, s46
	s_addc_u32 s47, s31, s47
	global_load_dword v65, v64, s[38:39]
	global_load_dwordx4 v[66:69], v169, s[46:47]
	global_load_dwordx4 v[74:77], v169, s[46:47] offset:16
	global_load_dwordx4 v[78:81], v169, s[46:47] offset:32
	global_load_dwordx4 v[82:85], v169, s[46:47] offset:48
	s_add_u32 s56, s46, 0x84000
	s_addc_u32 s57, s47, 0
	global_load_dwordx4 v[86:89], v169, s[56:57]
	global_load_dwordx4 v[90:93], v169, s[56:57] offset:16
	global_load_dwordx4 v[94:97], v169, s[56:57] offset:32
	global_load_dwordx4 v[98:101], v169, s[56:57] offset:48
	s_add_u32 s56, s46, 0x108000
	s_addc_u32 s57, s47, 0
	global_load_dwordx4 v[102:105], v169, s[56:57]
	global_load_dwordx4 v[106:109], v169, s[56:57] offset:16
	global_load_dwordx4 v[116:119], v169, s[56:57] offset:32
	global_load_dwordx4 v[126:129], v169, s[56:57] offset:48
	s_add_u32 s56, s46, 0x18c000
	s_addc_u32 s57, s47, 0
	global_load_dwordx4 v[130:133], v169, s[56:57]
	global_load_dwordx4 v[134:137], v169, s[56:57] offset:16
	global_load_dwordx4 v[138:141], v169, s[56:57] offset:32
	global_load_dwordx4 v[142:145], v169, s[56:57] offset:48
	global_load_dword v70, v64, s[4:5]
	global_load_dword v71, v64, s[4:5] offset:2048
	s_add_u32 s56, s4, 0x1000
	s_addc_u32 s57, s5, 0
	global_load_dword v110, v64, s[56:57]
	global_load_dword v111, v64, s[56:57] offset:2048
	s_add_u32 s56, s4, 0x2000
	s_addc_u32 s57, s5, 0
	global_load_dword v125, v64, s[56:57]
	global_load_dword v146, v64, s[56:57] offset:2048
	s_add_u32 s56, s4, 0x3000
	s_addc_u32 s57, s5, 0
	global_load_dword v147, v64, s[56:57]
	global_load_dword v148, v64, s[56:57] offset:2048
	s_add_u32 s56, s4, 0x4000
	s_addc_u32 s57, s5, 0
	global_load_dword v149, v64, s[56:57]
	global_load_dword v150, v64, s[56:57] offset:2048
	s_add_u32 s56, s4, 0x5000
	s_addc_u32 s57, s5, 0
	global_load_dword v151, v64, s[56:57]
	global_load_dword v152, v64, s[56:57] offset:2048
	s_add_u32 s56, s4, 0x6000
	s_addc_u32 s57, s5, 0
	global_load_dword v153, v64, s[56:57]
	global_load_dword v154, v64, s[56:57] offset:2048
	s_add_u32 s56, s4, 0x7000
	s_addc_u32 s57, s5, 0
	global_load_dword v155, v64, s[56:57]
	global_load_dword v156, v64, s[56:57] offset:2048
	s_mul_i32 s98, s8, 0x6400
	s_add_u32 s98, s22, s98
	s_addc_u32 s99, s23, 0
	s_add_u32 s98, s98, 0x3000
	s_addc_u32 s99, s99, 0
	global_load_dword v157, v64, s[98:99] offset:2048
	global_load_dword v161, v64, s[98:99]
	s_add_u32 s56, s98, 0x320000
	s_addc_u32 s57, s99, 0
	global_load_dword v158, v64, s[56:57] offset:2048
	global_load_dword v162, v64, s[56:57]
	s_add_u32 s56, s98, 0x640000
	s_addc_u32 s57, s99, 0
	global_load_dword v159, v64, s[56:57] offset:2048
	global_load_dword v163, v64, s[56:57]
	s_add_u32 s56, s98, 0x960000
	s_addc_u32 s57, s99, 0
	global_load_dword v160, v64, s[56:57] offset:2048
	global_load_dword v164, v64, s[56:57]
	s_waitcnt vmcnt(0)
	v_add_f32_e32 v165, 0, v66
	v_add_f32_e32 v165, v165, v86
	v_add_f32_e32 v165, v165, v102
	v_add_f32_e32 v165, v165, v130
	v_fmac_f32_e32 v65, v165, v70
	v_add_f32_e32 v165, 0, v67
	v_add_f32_e32 v165, v165, v87
	v_add_f32_e32 v165, v165, v103
	v_add_f32_e32 v165, v165, v131
	v_fmac_f32_e32 v65, v165, v71
	v_add_f32_e32 v165, 0, v68
	v_add_f32_e32 v165, v165, v88
	v_add_f32_e32 v165, v165, v104
	v_add_f32_e32 v165, v165, v132
	v_fmac_f32_e32 v65, v165, v110
	v_add_f32_e32 v165, 0, v69
	v_add_f32_e32 v165, v165, v89
	v_add_f32_e32 v165, v165, v105
	v_add_f32_e32 v165, v165, v133
	v_fmac_f32_e32 v65, v165, v111
	v_add_f32_e32 v165, 0, v74
	v_add_f32_e32 v165, v165, v90
	v_add_f32_e32 v165, v165, v106
	v_add_f32_e32 v165, v165, v134
	v_fmac_f32_e32 v65, v165, v125
	v_add_f32_e32 v165, 0, v75
	v_add_f32_e32 v165, v165, v91
	v_add_f32_e32 v165, v165, v107
	v_add_f32_e32 v165, v165, v135
	v_fmac_f32_e32 v65, v165, v146
	v_add_f32_e32 v165, 0, v76
	v_add_f32_e32 v165, v165, v92
	v_add_f32_e32 v165, v165, v108
	v_add_f32_e32 v165, v165, v136
	v_fmac_f32_e32 v65, v165, v147
	v_add_f32_e32 v165, 0, v77
	v_add_f32_e32 v165, v165, v93
	v_add_f32_e32 v165, v165, v109
	v_add_f32_e32 v165, v165, v137
	v_fmac_f32_e32 v65, v165, v148
	v_add_f32_e32 v165, 0, v78
	v_add_f32_e32 v165, v165, v94
	v_add_f32_e32 v165, v165, v116
	v_add_f32_e32 v165, v165, v138
	v_fmac_f32_e32 v65, v165, v149
	v_add_f32_e32 v165, 0, v79
	v_add_f32_e32 v165, v165, v95
	v_add_f32_e32 v165, v165, v117
	v_add_f32_e32 v165, v165, v139
	v_fmac_f32_e32 v65, v165, v150
	v_add_f32_e32 v165, 0, v80
	v_add_f32_e32 v165, v165, v96
	v_add_f32_e32 v165, v165, v118
	v_add_f32_e32 v165, v165, v140
	v_fmac_f32_e32 v65, v165, v151
	v_add_f32_e32 v165, 0, v81
	v_add_f32_e32 v165, v165, v97
	v_add_f32_e32 v165, v165, v119
	v_add_f32_e32 v165, v165, v141
	v_fmac_f32_e32 v65, v165, v152
	v_add_f32_e32 v165, 0, v82
	v_add_f32_e32 v165, v165, v98
	v_add_f32_e32 v165, v165, v126
	v_add_f32_e32 v165, v165, v142
	v_fmac_f32_e32 v65, v165, v153
	v_add_f32_e32 v165, 0, v83
	v_add_f32_e32 v165, v165, v99
	v_add_f32_e32 v165, v165, v127
	v_add_f32_e32 v165, v165, v143
	v_fmac_f32_e32 v65, v165, v154
	v_add_f32_e32 v165, 0, v84
	v_add_f32_e32 v165, v165, v100
	v_add_f32_e32 v165, v165, v128
	v_add_f32_e32 v165, v165, v144
	v_fmac_f32_e32 v65, v165, v155
	v_add_f32_e32 v165, 0, v85
	v_add_f32_e32 v165, v165, v101
	v_add_f32_e32 v165, v165, v129
	v_add_f32_e32 v165, v165, v145
	v_fmac_f32_e32 v65, v165, v156
	v_mul_f32_e64 v166, |v65|, s17
	v_exp_f32_e32 v166, v166
	v_min_f32_e32 v167, 0, v65
	v_add_f32_e32 v166, 1.0, v166
	v_cmp_gt_f32_e32 vcc, s14, v166
	s_nop 1
	v_cndmask_b32_e64 v168, 0, 32, vcc
	v_ldexp_f32 v166, v166, v168
	v_log_f32_e32 v166, v166
	s_nop 0
	v_mul_f32_e32 v168, 0x3f317217, v166
	v_fma_f32 v168, v166, s18, -v168
	v_fmac_f32_e32 v168, 0x3377d1cf, v166
	v_fmac_f32_e32 v168, 0x3f317217, v166
	v_cmp_lt_f32_e64 s[46:47], |v166|, s19
	s_nop 1
	v_cndmask_b32_e64 v166, v166, v168, s[46:47]
	v_cndmask_b32_e32 v168, 0, v218, vcc
	v_sub_f32_e32 v166, v166, v168
	v_sub_f32_e32 v167, v167, v166
	v_mul_f32_e32 v167, 0x3d800000, v167
	v_mul_f32_e32 v167, 0x3fb8aa3b, v167
	v_exp_f32_e32 v178, v167
	v_add_f32_e32 v166, 0, v157
	v_add_f32_e32 v166, v166, v158
	v_add_f32_e32 v166, v166, v159
	v_add_f32_e32 v166, v166, v160
	v_add_f32_e32 v167, 0, v161
	v_add_f32_e32 v167, v167, v162
	v_add_f32_e32 v167, v167, v163
	v_add_f32_e32 v167, v167, v164
	v_mul_f32_e32 v167, 0x3db504f3, v167
	ds_write2st64_b32 v122, v178, v166 offset1:2
	ds_write_b32 v122, v167 offset:1024
; template <bool WITH_O> __device__ __forceinline__ void gla_sample(LAS unsigned char* lds, int uidx, const float* PRS, const float* GLRP, const float* w2, const float* gb, const float* gn, ...
;     ...
;     const int dv4 = (tid & 63) * 4; const f32x4 v = prs_sum4(PRS, s, 4096 + h * DV + dv4);
;     __syncthreads();
;     f32x4 o = {0.f, 0.f, 0.f, 0.f};
; #pragma unroll
;     for (int kk = 0; kk < 16; ++kk) { const int k = 16 * wid + kk; const f32x4 sn = S[kk] * smA[k] + v * smK[k]; if (!WITH_O || !DEFER_STATE) __builtin_nontemporal_store(sn, (f32x4*)(s_out + sb + (size_t)k * DV)); if (WITH_O) o += sn * smQ[k]; }
.LBB0_362:
	s_or_b64 exec, exec, s[52:53]
	s_lshl_b32 s48, s6, 8
	v_or_b32_e32 v64, s48, v121
	v_lshlrev_b32_e32 v168, 2, v64
	v_mov_b32_e32 v78, s10
	s_mov_b32 s6, 0x4768000
	s_waitcnt lgkmcnt(0)
	s_barrier
	ds_read_b128 v[80:83], v78 offset:512
	s_waitcnt vmcnt(0)
	v_pk_add_f32 v[74:75], v[180:181], 0 op_sel_hi:[1,0]
	v_pk_add_f32 v[70:71], v[182:183], 0 op_sel_hi:[1,0]
	v_pk_add_f32 v[74:75], v[74:75], v[184:185]
	v_pk_add_f32 v[70:71], v[70:71], v[186:187]
	v_pk_add_f32 v[76:77], v[74:75], v[188:189]
	v_pk_add_f32 v[70:71], v[70:71], v[190:191]
	v_pk_add_f32 v[74:75], v[70:71], v[194:195]
	v_pk_add_f32 v[76:77], v[76:77], v[192:193]
	ds_read_b128 v[84:87], v78
	ds_read_b128 v[68:71], v78 offset:16
	ds_read_b128 v[64:67], v78 offset:32
	s_waitcnt lgkmcnt(3)
	v_pk_mul_f32 v[88:89], v[74:75], v[80:81] op_sel_hi:[1,0]
	v_pk_mul_f32 v[92:93], v[76:77], v[80:81] op_sel_hi:[1,0]
	s_waitcnt lgkmcnt(2)
	v_pk_fma_f32 v[90:91], v[62:63], v[84:85], v[88:89] op_sel_hi:[1,0,1]
	v_pk_fma_f32 v[88:89], v[60:61], v[84:85], v[92:93] op_sel_hi:[1,0,1]
	v_lshl_add_u64 v[60:61], s[28:29], 0, v[114:115]
	ds_read_b128 v[92:95], v78 offset:1024
	v_add_co_u32_e32 v96, vcc, s6, v60
	s_mov_b32 s6, 0x4769000
	s_nop 0
	v_addc_co_u32_e32 v97, vcc, 0, v61, vcc
	v_add_co_u32_e32 v62, vcc, s6, v60
	v_pk_mul_f32 v[98:99], v[74:75], v[80:81] op_sel:[0,1]
	s_nop 0
	v_addc_co_u32_e32 v63, vcc, 0, v61, vcc
	v_pk_mul_f32 v[80:81], v[76:77], v[80:81] op_sel:[0,1]
	global_store_dwordx4 v[62:63], v[88:91], off offset:-4096 nt
	v_pk_fma_f32 v[58:59], v[58:59], v[84:85], v[98:99] op_sel:[0,1,0]
	v_pk_fma_f32 v[56:57], v[56:57], v[84:85], v[80:81] op_sel:[0,1,0]
	s_waitcnt lgkmcnt(0)
	v_pk_fma_f32 v[88:89], v[88:89], v[92:93], 0 op_sel_hi:[1,0,0]
	v_pk_mul_f32 v[80:81], v[74:75], v[82:83] op_sel_hi:[1,0]
	v_pk_mul_f32 v[84:85], v[76:77], v[82:83] op_sel_hi:[1,0]
	v_pk_fma_f32 v[90:91], v[90:91], v[92:93], 0 op_sel_hi:[1,0,0]
	global_store_dwordx4 v[96:97], v[56:59], off offset:1024 nt
	v_pk_fma_f32 v[54:55], v[54:55], v[86:87], v[80:81] op_sel_hi:[1,0,1]
	v_pk_fma_f32 v[52:53], v[52:53], v[86:87], v[84:85] op_sel_hi:[1,0,1]
	v_pk_fma_f32 v[56:57], v[56:57], v[92:93], v[88:89] op_sel:[0,1,0]
	v_pk_fma_f32 v[58:59], v[58:59], v[92:93], v[90:91] op_sel:[0,1,0]
	global_store_dwordx4 v[96:97], v[52:55], off offset:2048 nt
	v_mov_b32_e32 v80, v87
	s_mov_b32 s6, 0x476a000
	v_pk_fma_f32 v[52:53], v[52:53], v[94:95], v[56:57] op_sel_hi:[1,0,1]
	v_mov_b32_e32 v56, v83
	v_pk_fma_f32 v[54:55], v[54:55], v[94:95], v[58:59] op_sel_hi:[1,0,1]
	v_pk_mul_f32 v[58:59], v[74:75], v[56:57] op_sel_hi:[1,0]
	v_pk_mul_f32 v[56:57], v[76:77], v[56:57] op_sel_hi:[1,0]
	v_pk_fma_f32 v[50:51], v[50:51], v[80:81], v[58:59] op_sel_hi:[1,0,1]
	v_pk_fma_f32 v[48:49], v[48:49], v[80:81], v[56:57] op_sel_hi:[1,0,1]
	v_mov_b32_e32 v56, v95
	global_store_dwordx4 v[96:97], v[48:51], off offset:3072 nt
	v_pk_fma_f32 v[58:59], v[50:51], v[56:57], v[54:55] op_sel_hi:[1,0,1]
	v_pk_fma_f32 v[56:57], v[48:49], v[56:57], v[52:53] op_sel_hi:[1,0,1]
	ds_read_b128 v[48:51], v78 offset:528
	s_waitcnt lgkmcnt(0)
	v_pk_mul_f32 v[52:53], v[74:75], v[48:49] op_sel_hi:[1,0]
	v_pk_mul_f32 v[54:55], v[76:77], v[48:49] op_sel_hi:[1,0]
	v_pk_fma_f32 v[46:47], v[46:47], v[68:69], v[52:53] op_sel_hi:[1,0,1]
	v_pk_fma_f32 v[44:45], v[44:45], v[68:69], v[54:55] op_sel_hi:[1,0,1]
	ds_read_b128 v[52:55], v78 offset:1040
	global_store_dwordx4 v[62:63], v[44:47], off nt
	s_waitcnt lgkmcnt(0)
	s_nop 0
	v_pk_fma_f32 v[44:45], v[44:45], v[52:53], v[56:57] op_sel_hi:[1,0,1]
	v_pk_mul_f32 v[56:57], v[74:75], v[48:49] op_sel:[0,1]
	v_pk_mul_f32 v[48:49], v[76:77], v[48:49] op_sel:[0,1]
	v_pk_fma_f32 v[46:47], v[46:47], v[52:53], v[58:59] op_sel_hi:[1,0,1]
	v_pk_fma_f32 v[42:43], v[42:43], v[68:69], v[56:57] op_sel:[0,1,0]
	v_pk_fma_f32 v[40:41], v[40:41], v[68:69], v[48:49] op_sel:[0,1,0]
	global_store_dwordx4 v[62:63], v[40:43], off offset:1024 nt
	s_nop 1
	v_pk_fma_f32 v[42:43], v[42:43], v[52:53], v[46:47] op_sel:[0,1,0]
	v_pk_fma_f32 v[40:41], v[40:41], v[52:53], v[44:45] op_sel:[0,1,0]
	v_pk_mul_f32 v[44:45], v[74:75], v[50:51] op_sel_hi:[1,0]
	v_pk_mul_f32 v[46:47], v[76:77], v[50:51] op_sel_hi:[1,0]
	v_pk_fma_f32 v[38:39], v[38:39], v[70:71], v[44:45] op_sel_hi:[1,0,1]
	v_pk_fma_f32 v[36:37], v[36:37], v[70:71], v[46:47] op_sel_hi:[1,0,1]
	global_store_dwordx4 v[62:63], v[36:39], off offset:2048 nt
	v_mov_b32_e32 v44, v71
	s_nop 0
	v_pk_fma_f32 v[36:37], v[36:37], v[54:55], v[40:41] op_sel_hi:[1,0,1]
	v_mov_b32_e32 v40, v51
	v_pk_fma_f32 v[38:39], v[38:39], v[54:55], v[42:43] op_sel_hi:[1,0,1]
	v_pk_mul_f32 v[42:43], v[74:75], v[40:41] op_sel_hi:[1,0]
	v_pk_mul_f32 v[40:41], v[76:77], v[40:41] op_sel_hi:[1,0]
	v_pk_fma_f32 v[34:35], v[34:35], v[44:45], v[42:43] op_sel_hi:[1,0,1]
	v_pk_fma_f32 v[32:33], v[32:33], v[44:45], v[40:41] op_sel_hi:[1,0,1]
	v_mov_b32_e32 v40, v55
	global_store_dwordx4 v[62:63], v[32:35], off offset:3072 nt
	v_pk_fma_f32 v[44:45], v[34:35], v[40:41], v[38:39] op_sel_hi:[1,0,1]
	v_pk_fma_f32 v[46:47], v[32:33], v[40:41], v[36:37] op_sel_hi:[1,0,1]
	ds_read_b128 v[32:35], v78 offset:544
	s_waitcnt lgkmcnt(0)
	v_pk_mul_f32 v[36:37], v[74:75], v[32:33] op_sel_hi:[1,0]
	v_pk_mul_f32 v[40:41], v[76:77], v[32:33] op_sel_hi:[1,0]
	v_pk_fma_f32 v[38:39], v[30:31], v[64:65], v[36:37] op_sel_hi:[1,0,1]
	v_pk_fma_f32 v[36:37], v[28:29], v[64:65], v[40:41] op_sel_hi:[1,0,1]
	ds_read_b128 v[40:43], v78 offset:1056
	v_add_co_u32_e32 v30, vcc, s6, v60
	s_mov_b32 s6, 0x476b000
	s_nop 0
	v_addc_co_u32_e32 v31, vcc, 0, v61, vcc
	v_add_co_u32_e32 v28, vcc, s6, v60
	s_nop 1
	v_addc_co_u32_e32 v29, vcc, 0, v61, vcc
	global_store_dwordx4 v[28:29], v[36:39], off offset:-4096 nt
	s_waitcnt lgkmcnt(0)
; #define LAS __attribute__((address_space(3)))
; template <bool WITH_O> __device__ __forceinline__ void gla_sample(LAS unsigned char* lds, int uidx, const float* PRS, const float* GLRP, const float* w2, const float* gb, const float* gn, ...
;     ...
;     for (int kk = 0; kk < 16; ++kk) { const int k = 16 * wid + kk; const f32x4 sn = S[kk] * smA[k] + v * smK[k]; if (!WITH_O || !DEFER_STATE) __builtin_nontemporal_store(sn, (f32x4*)(s_out + sb + (size_t)k * DV)); if (WITH_O) o += sn * smQ[k]; }
;     if (!WITH_O) { __syncthreads(); return; }
;     *(LAS f32x4*)(smO + wid * 256 + dv4) = o;
;     __syncthreads();
;     float oo = 0.f;
;     if (tid < 256) {
; #pragma unroll
;         for (int w = 0; w < 8; ++w) oo += smO[w * 256 + tid];
;         const float ss = wave_sum(oo * oo); if (lane == 0) smR[wid] = ss; }
	s_nop 0
	v_pk_fma_f32 v[38:39], v[38:39], v[40:41], v[44:45] op_sel_hi:[1,0,1]
	v_pk_mul_f32 v[44:45], v[74:75], v[32:33] op_sel:[0,1]
	v_pk_mul_f32 v[32:33], v[76:77], v[32:33] op_sel:[0,1]
	v_pk_fma_f32 v[36:37], v[36:37], v[40:41], v[46:47] op_sel_hi:[1,0,1]
	v_pk_fma_f32 v[26:27], v[26:27], v[64:65], v[44:45] op_sel:[0,1,0]
	v_pk_fma_f32 v[24:25], v[24:25], v[64:65], v[32:33] op_sel:[0,1,0]
	global_store_dwordx4 v[30:31], v[24:27], off offset:1024 nt
	v_pk_mul_f32 v[32:33], v[74:75], v[34:35] op_sel_hi:[1,0]
	s_nop 0
	v_pk_fma_f32 v[24:25], v[24:25], v[40:41], v[36:37] op_sel:[0,1,0]
	v_pk_mul_f32 v[36:37], v[76:77], v[34:35] op_sel_hi:[1,0]
	v_pk_fma_f32 v[22:23], v[22:23], v[66:67], v[32:33] op_sel_hi:[1,0,1]
	v_pk_fma_f32 v[20:21], v[20:21], v[66:67], v[36:37] op_sel_hi:[1,0,1]
	v_pk_fma_f32 v[26:27], v[26:27], v[40:41], v[38:39] op_sel:[0,1,0]
	global_store_dwordx4 v[30:31], v[20:23], off offset:2048 nt
	v_pk_fma_f32 v[24:25], v[20:21], v[42:43], v[24:25] op_sel_hi:[1,0,1]
	v_mov_b32_e32 v32, v67
	v_mov_b32_e32 v20, v35
	v_pk_fma_f32 v[22:23], v[22:23], v[42:43], v[26:27] op_sel_hi:[1,0,1]
	v_pk_mul_f32 v[26:27], v[74:75], v[20:21] op_sel_hi:[1,0]
	v_pk_mul_f32 v[20:21], v[76:77], v[20:21] op_sel_hi:[1,0]
	v_pk_fma_f32 v[18:19], v[18:19], v[32:33], v[26:27] op_sel_hi:[1,0,1]
	v_pk_fma_f32 v[16:17], v[16:17], v[32:33], v[20:21] op_sel_hi:[1,0,1]
	global_store_dwordx4 v[30:31], v[16:19], off offset:3072 nt
	v_mov_b32_e32 v26, v43
	v_pk_fma_f32 v[20:21], v[18:19], v[26:27], v[22:23] op_sel_hi:[1,0,1]
	v_pk_fma_f32 v[22:23], v[16:17], v[26:27], v[24:25] op_sel_hi:[1,0,1]
	ds_read_b128 v[16:19], v78 offset:48
	ds_read_b128 v[24:27], v78 offset:560
	s_waitcnt lgkmcnt(0)
	v_pk_mul_f32 v[30:31], v[74:75], v[24:25] op_sel_hi:[1,0]
	v_pk_mul_f32 v[32:33], v[76:77], v[24:25] op_sel_hi:[1,0]
	v_pk_fma_f32 v[14:15], v[14:15], v[16:17], v[30:31] op_sel_hi:[1,0,1]
	v_pk_fma_f32 v[12:13], v[12:13], v[16:17], v[32:33] op_sel_hi:[1,0,1]
	ds_read_b128 v[30:33], v78 offset:1072
	global_store_dwordx4 v[28:29], v[12:15], off nt
	s_waitcnt lgkmcnt(0)
	s_nop 0
	v_pk_fma_f32 v[14:15], v[14:15], v[30:31], v[20:21] op_sel_hi:[1,0,1]
	v_pk_fma_f32 v[12:13], v[12:13], v[30:31], v[22:23] op_sel_hi:[1,0,1]
	v_pk_mul_f32 v[20:21], v[74:75], v[24:25] op_sel:[0,1]
	v_pk_mul_f32 v[22:23], v[76:77], v[24:25] op_sel:[0,1]
	v_pk_fma_f32 v[10:11], v[10:11], v[16:17], v[20:21] op_sel:[0,1,0]
	v_pk_fma_f32 v[8:9], v[8:9], v[16:17], v[22:23] op_sel:[0,1,0]
	global_store_dwordx4 v[28:29], v[8:11], off offset:1024 nt
	s_nop 1
	v_pk_fma_f32 v[10:11], v[10:11], v[30:31], v[14:15] op_sel:[0,1,0]
	v_pk_fma_f32 v[8:9], v[8:9], v[30:31], v[12:13] op_sel:[0,1,0]
	v_pk_mul_f32 v[12:13], v[74:75], v[26:27] op_sel_hi:[1,0]
	v_pk_mul_f32 v[14:15], v[76:77], v[26:27] op_sel_hi:[1,0]
	v_pk_fma_f32 v[6:7], v[6:7], v[18:19], v[12:13] op_sel_hi:[1,0,1]
	v_pk_fma_f32 v[4:5], v[4:5], v[18:19], v[14:15] op_sel_hi:[1,0,1]
	global_store_dwordx4 v[28:29], v[4:7], off offset:2048 nt
	v_mov_b32_e32 v12, v19
	s_nop 0
	v_pk_fma_f32 v[4:5], v[4:5], v[32:33], v[8:9] op_sel_hi:[1,0,1]
	v_mov_b32_e32 v8, v27
	v_pk_fma_f32 v[6:7], v[6:7], v[32:33], v[10:11] op_sel_hi:[1,0,1]
	v_pk_mul_f32 v[10:11], v[74:75], v[8:9] op_sel_hi:[1,0]
	v_pk_mul_f32 v[8:9], v[76:77], v[8:9] op_sel_hi:[1,0]
	v_pk_fma_f32 v[2:3], v[2:3], v[12:13], v[10:11] op_sel_hi:[1,0,1]
	v_pk_fma_f32 v[0:1], v[0:1], v[12:13], v[8:9] op_sel_hi:[1,0,1]
	v_mov_b32_e32 v8, v33
	global_store_dwordx4 v[28:29], v[0:3], off offset:3072 nt
	s_nop 1
	v_pk_fma_f32 v[2:3], v[2:3], v[8:9], v[6:7] op_sel_hi:[1,0,1]
	v_pk_fma_f32 v[0:1], v[0:1], v[8:9], v[4:5] op_sel_hi:[1,0,1]
	ds_write_b128 v123, v[0:3] offset:1536
	v_mov_b32_e32 v0, 0
	s_add_i32 s100, s55, s82
	s_cmpk_gt_i32 s100, 0x1ff
	s_cbranch_scc1 .Lgs_nopf
	s_add_u32 s100, s24, s36
	s_addc_u32 s101, s25, s37
	global_load_dwordx4 v[60:63], v114, s[100:101] nt
	global_load_dwordx4 v[56:59], v114, s[100:101] offset:1024 nt
	global_load_dwordx4 v[52:55], v114, s[100:101] offset:2048 nt
	global_load_dwordx4 v[48:51], v114, s[100:101] offset:3072 nt
	s_add_u32 s100, s100, 0x1000
	s_addc_u32 s101, s101, 0
	global_load_dwordx4 v[44:47], v114, s[100:101] nt
	global_load_dwordx4 v[40:43], v114, s[100:101] offset:1024 nt
	global_load_dwordx4 v[36:39], v114, s[100:101] offset:2048 nt
	global_load_dwordx4 v[32:35], v114, s[100:101] offset:3072 nt
	s_add_u32 s100, s100, 0x1000
	s_addc_u32 s101, s101, 0
	global_load_dwordx4 v[28:31], v114, s[100:101] nt
	global_load_dwordx4 v[24:27], v114, s[100:101] offset:1024 nt
	global_load_dwordx4 v[20:23], v114, s[100:101] offset:2048 nt
	global_load_dwordx4 v[16:19], v114, s[100:101] offset:3072 nt
	s_add_u32 s100, s100, 0x1000
	s_addc_u32 s101, s101, 0
	global_load_dwordx4 v[12:15], v114, s[100:101] nt
	s_mov_b32 s79, 2
.Lgs_nopf:
	s_waitcnt lgkmcnt(0)
	s_barrier
	s_and_saveexec_b64 s[6:7], s[40:41]
	s_cbranch_execz .LBB0_366
	ds_read2st64_b32 v[0:1], v122 offset0:6 offset1:10
	v_xor_b32_e32 v3, 1, v211
	s_waitcnt lgkmcnt(0)
	v_add_f32_e32 v0, 0, v0
	v_add_f32_e32 v2, v0, v1
	ds_read2st64_b32 v[0:1], v122 offset0:14 offset1:18
	s_waitcnt lgkmcnt(0)
	v_add_f32_e32 v0, v2, v0
	v_add_f32_e32 v2, v0, v1
	ds_read2st64_b32 v[0:1], v122 offset0:22 offset1:26
	s_waitcnt lgkmcnt(0)
	v_add_f32_e32 v0, v2, v0
	v_add_f32_e32 v2, v0, v1
	ds_read2st64_b32 v[0:1], v122 offset0:30 offset1:34
	s_waitcnt lgkmcnt(0)
	v_add_f32_e32 v0, v2, v0
	v_and_b32_e32 v2, 64, v211
	v_add_u32_e32 v2, 64, v2
	v_cmp_lt_i32_e32 vcc, v3, v2
	v_add_f32_e32 v0, v0, v1
	v_mul_f32_e32 v1, v0, v0
	v_cndmask_b32_e32 v3, v211, v3, vcc
	v_lshlrev_b32_e32 v3, 2, v3
	ds_bpermute_b32 v1, v3, v1
	v_xor_b32_e32 v3, 2, v211
	v_cmp_lt_i32_e32 vcc, v3, v2
	s_waitcnt lgkmcnt(0)
	v_fmac_f32_e32 v1, v0, v0
	v_cndmask_b32_e32 v3, v211, v3, vcc
	v_lshlrev_b32_e32 v3, 2, v3
	ds_bpermute_b32 v3, v3, v1
	s_waitcnt lgkmcnt(0)
	v_add_f32_e32 v1, v1, v3
	v_xor_b32_e32 v3, 4, v211
	v_cmp_lt_i32_e32 vcc, v3, v2
	s_nop 1
	v_cndmask_b32_e32 v3, v211, v3, vcc
	v_lshlrev_b32_e32 v3, 2, v3
	ds_bpermute_b32 v3, v3, v1
	s_waitcnt lgkmcnt(0)
	v_add_f32_e32 v1, v1, v3
	v_xor_b32_e32 v3, 8, v211
	v_cmp_lt_i32_e32 vcc, v3, v2
	s_nop 1
	v_cndmask_b32_e32 v3, v211, v3, vcc
	v_lshlrev_b32_e32 v3, 2, v3
	ds_bpermute_b32 v3, v3, v1
	s_waitcnt lgkmcnt(0)
	v_add_f32_e32 v1, v1, v3
	v_xor_b32_e32 v3, 16, v211
	v_cmp_lt_i32_e32 vcc, v3, v2
	s_nop 1
	v_cndmask_b32_e32 v3, v211, v3, vcc
	v_lshlrev_b32_e32 v3, 2, v3
	ds_bpermute_b32 v3, v3, v1
	s_waitcnt lgkmcnt(0)
	v_add_f32_e32 v1, v1, v3
	v_xor_b32_e32 v3, 32, v211
	v_cmp_lt_i32_e32 vcc, v3, v2
	s_nop 1
	v_cndmask_b32_e32 v2, v211, v3, vcc
	v_lshlrev_b32_e32 v2, 2, v2
	ds_bpermute_b32 v2, v2, v1
	s_and_saveexec_b64 s[8:9], s[44:45]
	s_cbranch_execz .LBB0_365
	s_waitcnt lgkmcnt(0)
	v_add_f32_e32 v1, v1, v2
	v_mov_b32_e32 v2, s54
	ds_write_b32 v2, v1 offset:9728
